# v67 + sample attention: tile T+2 loads issued right after the landing-set copy at the loop top (before the convert / LDS write / barrier)
# baseline (speedup 1.0000x reference)
.Lsa_copied:
	s_cmp_lt_u32 s34, 62
	s_cbranch_scc0 .Lsa_noload
	v_add_u32_e32 v226, 64, v96
	v_ashrrev_i32_e32 v227, 31, v226
	v_lshlrev_b64 v[226:227], 12, v[226:227]
	v_lshl_add_u64 v[228:229], v[92:93], 0, v[226:227]
	v_lshl_add_u64 v[230:231], v[94:95], 0, v[226:227]
	s_bitcmp1_b32 s34, 0
	s_cbranch_scc1 .Lsa_load1
	global_load_dwordx4 v[160:163], v[228:229], off offset:48
	global_load_dwordx4 v[164:167], v[228:229], off offset:32
	global_load_dwordx4 v[168:171], v[228:229], off offset:16
	global_load_dwordx4 v[172:175], v[228:229], off
	global_load_dwordx4 v[176:179], v[230:231], off offset:48
	global_load_dwordx4 v[180:183], v[230:231], off offset:32
	global_load_dwordx4 v[184:187], v[230:231], off offset:16
	global_load_dwordx4 v[188:191], v[230:231], off
	s_branch .Lsa_noload

.Lsa_noload:
	v_cvt_pk_bf16_f32 v56, v56, v57
	v_cvt_pk_bf16_f32 v57, v58, v59
	v_cvt_pk_bf16_f32 v59, v62, v63
	v_bfe_u32 v62, v54, 16, 1
	v_bfe_u32 v63, v55, 16, 1
	v_bfe_u32 v137, v40, 16, 1
	v_bfe_u32 v138, v41, 16, 1
	v_ashrrev_i32_e32 v97, 31, v96
	s_mul_i32 s7, s6, 0x4800
	v_cvt_pk_bf16_f32 v68, v68, v69
	v_cvt_pk_bf16_f32 v69, v70, v71
	v_cvt_pk_bf16_f32 v70, v64, v65
	v_cvt_pk_bf16_f32 v58, v60, v61
	v_bfe_u32 v60, v52, 16, 1
	v_bfe_u32 v61, v53, 16, 1
	v_bfe_u32 v64, v48, 16, 1
	v_bfe_u32 v65, v49, 16, 1
	v_bfe_u32 v139, v42, 16, 1
	v_bfe_u32 v140, v43, 16, 1
	s_lshl_b32 s6, s6, 10
	v_add3_u32 v54, v54, v62, s45
	v_add3_u32 v55, v55, v63, s45
	v_add3_u32 v62, v40, v137, s45
	v_add3_u32 v63, v41, v138, s45
	v_lshlrev_b64 v[40:41], 12, v[96:97]
	s_add_i32 s7, s7, 0
	v_mov_b32_e32 v150, v89
	v_mov_b32_e32 v89, v91
	v_cvt_pk_bf16_f32 v71, v66, v67
	v_bfe_u32 v91, v44, 16, 1
	v_bfe_u32 v134, v45, 16, 1
	v_bfe_u32 v135, v46, 16, 1
	v_bfe_u32 v136, v47, 16, 1
	v_add3_u32 v60, v52, v60, s45
	v_add3_u32 v61, v53, v61, s45
	v_add3_u32 v48, v48, v64, s45
	v_add3_u32 v49, v49, v65, s45
	v_add3_u32 v64, v42, v139, s45
	v_add3_u32 v65, v43, v140, s45
	v_lshl_add_u64 v[42:43], v[92:93], 0, v[40:41]
	v_lshl_add_u64 v[52:53], v[94:95], 0, v[40:41]
	s_sub_i32 s6, s7, s6
	v_add3_u32 v40, s7, v81, v98
	v_add_u32_e32 v41, s7, v101
	v_bfe_u32 v66, v50, 16, 1
	v_bfe_u32 v67, v51, 16, 1
	v_add3_u32 v44, v44, v91, s45
	v_add3_u32 v45, v45, v134, s45
	v_add3_u32 v46, v46, v135, s45
	v_add3_u32 v47, v47, v136, s45
	ds_write_b128 v40, v[68:71]
	ds_write_b128 v40, v[56:59] offset:16
	v_add3_u32 v40, s6, v99, v106
	v_add3_u32 v91, v41, v102, s42
	v_add3_u32 v50, v50, v66, s45
	v_add3_u32 v51, v51, v67, s45
	ds_write_b16_d16_hi v40, v60 offset:36864
	ds_write_b16_d16_hi v40, v61 offset:37000
	ds_write_b16_d16_hi v40, v54 offset:37136
	ds_write_b16_d16_hi v40, v55 offset:37272
	ds_write_b16_d16_hi v40, v48 offset:37408
	ds_write_b16_d16_hi v40, v49 offset:37544
	ds_write_b16_d16_hi v40, v50 offset:37680
	ds_write_b16_d16_hi v40, v51 offset:37816
	ds_write_b16_d16_hi v40, v44 offset:37952
	ds_write_b16_d16_hi v40, v45 offset:38088
	ds_write_b16_d16_hi v40, v46 offset:38224
	ds_write_b16_d16_hi v40, v47 offset:38360
	ds_write_b16_d16_hi v40, v62 offset:38496
	ds_write_b16_d16_hi v40, v63 offset:38632
	ds_write_b16_d16_hi v40, v64 offset:38768
	ds_write_b16_d16_hi v40, v65 offset:38904
	s_waitcnt lgkmcnt(0)
	s_barrier
	ds_read_b128 v[134:137], v91
	s_nop 0
	ds_read_b128 v[138:141], v91 offset:64
	s_nop 0
	s_waitcnt lgkmcnt(1)
	v_mfma_f32_16x16x32_bf16 v[134:137], v[134:137], v[0:3], 0
	s_add_i32 s6, s43, s6
	v_add3_u32 v97, s6, v72, v107
	ds_read_b64 v[142:143], v97 offset:36864
	s_waitcnt lgkmcnt(1)
	v_mfma_f32_16x16x32_bf16 v[134:137], v[138:141], v[4:7], v[134:137]
	ds_read_b64 v[144:145], v97 offset:39040
	ds_read_b64 v[146:147], v97 offset:41216
	ds_read_b64 v[148:149], v97 offset:43392
	s_add_i32 s34, s34, 1
	v_add_u32_e32 v96, 64, v96
	s_nop 2
	v_max_f32_e32 v91, v137, v137
	v_max_f32_e32 v138, v136, v136
	v_max_f32_e32 v91, v138, v91
	v_max3_f32 v91, v134, v135, v91
	ds_bpermute_b32 v138, v103, v91
	s_cmp_eq_u32 s34, 63
	s_waitcnt lgkmcnt(0)
	v_max_f32_e32 v138, v138, v138
	v_max_f32_e32 v91, v91, v138
	ds_bpermute_b32 v138, v104, v91
	s_waitcnt lgkmcnt(0)
	v_max3_f32 v91, v89, v91, v138
	v_sub_f32_e32 v89, v89, v91
	v_sub_f32_e32 v134, v134, v91
	v_sub_f32_e32 v135, v135, v91
	v_sub_f32_e32 v136, v136, v91
	v_sub_f32_e32 v137, v137, v91
	v_cmp_gt_f32_e32 vcc, s46, v89
	v_cmp_gt_f32_e64 s[6:7], s46, v134
	v_cmp_gt_f32_e64 s[8:9], s46, v135
	v_cmp_gt_f32_e64 s[10:11], s46, v136
	v_cmp_gt_f32_e64 s[12:13], s46, v137
	v_cndmask_b32_e32 v138, 0, v130, vcc
	v_cndmask_b32_e64 v139, 0, v130, s[6:7]
	v_cndmask_b32_e64 v140, 0, v130, s[8:9]
	v_cndmask_b32_e64 v141, 0, v130, s[10:11]
	v_cndmask_b32_e64 v151, 0, v130, s[12:13]
	v_add_f32_e32 v89, v89, v138
	v_add_f32_e32 v134, v134, v139
	v_add_f32_e32 v135, v135, v140
	v_add_f32_e32 v136, v136, v141
	v_add_f32_e32 v137, v137, v151
	v_exp_f32_e32 v89, v89
	v_exp_f32_e32 v152, v134
	v_exp_f32_e32 v135, v135
	v_exp_f32_e32 v153, v136
	v_exp_f32_e32 v154, v137
	v_cndmask_b32_e32 v138, 0, v131, vcc
	v_cndmask_b32_e64 v139, 0, v131, s[6:7]
	v_cndmask_b32_e64 v140, 0, v131, s[8:9]
	v_cndmask_b32_e64 v141, 0, v131, s[10:11]
	v_cndmask_b32_e64 v151, 0, v131, s[12:13]
	v_ldexp_f32 v134, v89, v138
	v_ldexp_f32 v136, v152, v139
	v_ldexp_f32 v138, v135, v140
	v_ldexp_f32 v137, v153, v141
	v_ldexp_f32 v139, v154, v151
	v_cvt_pk_bf16_f32 v140, v136, v138
	v_cvt_pk_bf16_f32 v141, v137, v139
	v_pk_mul_f32 v[38:39], v[38:39], v[134:135] op_sel_hi:[1,0]
	v_pk_mul_f32 v[36:37], v[36:37], v[134:135] op_sel_hi:[1,0]
	v_pk_mul_f32 v[34:35], v[34:35], v[134:135] op_sel_hi:[1,0]
	v_pk_mul_f32 v[32:33], v[32:33], v[134:135] op_sel_hi:[1,0]
	v_pk_mul_f32 v[30:31], v[30:31], v[134:135] op_sel_hi:[1,0]
	v_pk_mul_f32 v[28:29], v[28:29], v[134:135] op_sel_hi:[1,0]
	v_pk_mul_f32 v[26:27], v[26:27], v[134:135] op_sel_hi:[1,0]
	v_pk_mul_f32 v[24:25], v[24:25], v[134:135] op_sel_hi:[1,0]
	v_mfma_f32_16x16x16_bf16 v[36:39], v[142:143], v[140:141], v[36:39]
	ds_read_b64 v[142:143], v97 offset:45568
	v_pk_mul_f32 v[22:23], v[22:23], v[134:135] op_sel_hi:[1,0]
	v_pk_mul_f32 v[20:21], v[20:21], v[134:135] op_sel_hi:[1,0]
	v_mfma_f32_16x16x16_bf16 v[32:35], v[144:145], v[140:141], v[32:35]
	ds_read_b64 v[144:145], v97 offset:47744
	v_pk_mul_f32 v[10:11], v[10:11], v[134:135] op_sel_hi:[1,0]
	v_pk_mul_f32 v[8:9], v[8:9], v[134:135] op_sel_hi:[1,0]
	v_mfma_f32_16x16x16_bf16 v[28:31], v[146:147], v[140:141], v[28:31]
	ds_read_b64 v[146:147], v97 offset:49920
	v_pk_mul_f32 v[18:19], v[18:19], v[134:135] op_sel_hi:[1,0]
	v_pk_mul_f32 v[16:17], v[16:17], v[134:135] op_sel_hi:[1,0]
	v_mfma_f32_16x16x16_bf16 v[24:27], v[148:149], v[140:141], v[24:27]
	ds_read_b64 v[148:149], v97 offset:52096
	v_pk_mul_f32 v[14:15], v[14:15], v[134:135] op_sel_hi:[1,0]
	v_pk_mul_f32 v[12:13], v[12:13], v[134:135] op_sel_hi:[1,0]
	s_waitcnt lgkmcnt(3)
	v_mfma_f32_16x16x16_bf16 v[20:23], v[142:143], v[140:141], v[20:23]
	v_add_f32_e64 v136, v136, v138
	v_add_f32_e64 v137, v137, v139
	v_add_f32_e32 v89, v136, v137
	s_waitcnt lgkmcnt(2)
	v_mfma_f32_16x16x16_bf16 v[8:11], v[144:145], v[140:141], v[8:11]
	v_fmac_f32_e32 v89, v150, v134
	s_waitcnt lgkmcnt(1)
	v_mfma_f32_16x16x16_bf16 v[16:19], v[146:147], v[140:141], v[16:19]
	s_waitcnt lgkmcnt(0)
	v_mfma_f32_16x16x16_bf16 v[12:15], v[148:149], v[140:141], v[12:15]
	s_cbranch_scc0 .LBB0_1022
	s_waitcnt vmcnt(0)
	v_mov_b64_e32 v[60:61], v[192:193]
	v_mov_b64_e32 v[62:63], v[194:195]
	v_mov_b64_e32 v[56:57], v[196:197]
	v_mov_b64_e32 v[58:59], v[198:199]
	v_mov_b64_e32 v[64:65], v[200:201]
	v_mov_b64_e32 v[66:67], v[202:203]
	v_mov_b64_e32 v[68:69], v[204:205]
	v_mov_b64_e32 v[70:71], v[206:207]
	v_mov_b64_e32 v[40:41], v[208:209]
	v_mov_b64_e32 v[42:43], v[210:211]
	v_mov_b64_e32 v[44:45], v[212:213]
	v_mov_b64_e32 v[46:47], v[214:215]
	v_mov_b64_e32 v[48:49], v[216:217]
	v_mov_b64_e32 v[50:51], v[218:219]
	v_mov_b64_e32 v[52:53], v[220:221]
	v_mov_b64_e32 v[54:55], v[222:223]
	v_add_u32_e32 v94, v80, v98
	s_waitcnt vmcnt(6)
	v_cvt_pk_bf16_f32 v56, v56, v57
	v_cvt_pk_bf16_f32 v57, v58, v59
	v_cvt_pk_bf16_f32 v58, v60, v61
	v_cvt_pk_bf16_f32 v59, v62, v63
	ds_write_b128 v94, v[56:59] offset:18448
	s_waitcnt vmcnt(0)
	v_bfe_u32 v56, v52, 16, 1
	v_cvt_pk_bf16_f32 v68, v68, v69
	v_cvt_pk_bf16_f32 v69, v70, v71
	v_cvt_pk_bf16_f32 v70, v64, v65
	v_cvt_pk_bf16_f32 v71, v66, v67
	v_add3_u32 v52, v52, v56, s45
	ds_write_b128 v94, v[68:71] offset:18432
	ds_write_b16_d16_hi v132, v52 offset:54272
	v_bfe_u32 v52, v53, 16, 1
	v_add3_u32 v52, v53, v52, s45
	ds_write_b16_d16_hi v132, v52 offset:54408
	v_bfe_u32 v52, v54, 16, 1
	v_add3_u32 v52, v54, v52, s45
	ds_write_b16_d16_hi v132, v52 offset:54544
	v_bfe_u32 v52, v55, 16, 1
	v_add3_u32 v52, v55, v52, s45
	ds_write_b16_d16_hi v132, v52 offset:54680
	v_bfe_u32 v52, v48, 16, 1
	v_add3_u32 v48, v48, v52, s45
	ds_write_b16_d16_hi v132, v48 offset:54816
	v_bfe_u32 v48, v49, 16, 1
	v_add3_u32 v48, v49, v48, s45
	ds_write_b16_d16_hi v132, v48 offset:54952
	v_bfe_u32 v48, v50, 16, 1
	v_add3_u32 v48, v50, v48, s45
	ds_write_b16_d16_hi v132, v48 offset:55088
	v_bfe_u32 v48, v51, 16, 1
	v_add3_u32 v48, v51, v48, s45
	ds_write_b16_d16_hi v132, v48 offset:55224
	v_bfe_u32 v48, v44, 16, 1
	v_add3_u32 v44, v44, v48, s45
	ds_write_b16_d16_hi v132, v44 offset:55360
	v_bfe_u32 v44, v45, 16, 1
	v_add3_u32 v44, v45, v44, s45
	ds_write_b16_d16_hi v132, v44 offset:55496
	v_bfe_u32 v44, v46, 16, 1
	v_add3_u32 v44, v46, v44, s45
	ds_write_b16_d16_hi v132, v44 offset:55632
	v_bfe_u32 v44, v47, 16, 1
	v_add3_u32 v44, v47, v44, s45
	ds_write_b16_d16_hi v132, v44 offset:55768
	v_bfe_u32 v44, v40, 16, 1
	v_add3_u32 v40, v40, v44, s45
	ds_write_b16_d16_hi v132, v40 offset:55904
	v_bfe_u32 v40, v41, 16, 1
	v_add3_u32 v40, v41, v40, s45
	v_or_b32_e32 v92, s33, v100
	ds_write_b16_d16_hi v132, v40 offset:56040
	v_bfe_u32 v40, v42, 16, 1
	v_ashrrev_i32_e32 v93, 31, v92
	v_add3_u32 v40, v42, v40, s45
	v_lshlrev_b64 v[92:93], 12, v[92:93]
	ds_write_b16_d16_hi v132, v40 offset:56176
	v_bfe_u32 v40, v43, 16, 1
	v_lshl_add_u64 v[96:97], s[22:23], 0, v[92:93]
	v_add3_u32 v40, v43, v40, s45
	ds_write_b16_d16_hi v132, v40 offset:56312
	v_lshl_add_u64 v[40:41], v[96:97], 0, s[38:39]
	v_lshl_add_u64 v[62:63], v[40:41], 0, v[74:75]
	v_mov_b32_e32 v40, 0
	v_mov_b32_e32 v44, 0
	v_mov_b32_e32 v45, 0
	v_mov_b32_e32 v46, 0
	v_mov_b32_e32 v47, 0
	s_waitcnt lgkmcnt(0)
	s_barrier
	s_and_saveexec_b64 s[6:7], s[2:3]
	s_cbranch_execz .LBB0_1025
	global_load_dwordx4 v[44:47], v[62:63], off
